# merge<1> (sample rows): the 4 gate loads of each branch epilogue issued together
# speedup vs baseline: 1.0084x; 1.0084x over previous
.LBB0_2047:
	s_cmpk_eq_i32 s10, 0x800
	s_cselect_b32 s5, s30, 0x1b0
	s_cselect_b32 s12, s31, 0xf8
	s_cmp_eq_u32 s10, 0
	s_cselect_b32 s5, 0x1a0, s5
	s_cselect_b32 s21, 0xe8, s12
	s_add_u32 s12, s0, s5
	s_addc_u32 s13, s1, 0
	s_add_u32 s22, s0, s21
	s_addc_u32 s23, s1, 0
	s_load_dwordx2 s[12:13], s[12:13], 0x0
	v_mov_b32_e32 v40, v196
	s_load_dwordx2 s[22:23], s[22:23], 0x0
	s_waitcnt lgkmcnt(0)
	v_bfe_u32 v28, v40, 3, 3
	v_bfe_u32 v42, v40, 4, 2
	s_add_u32 s5, s22, s20
	s_addc_u32 s21, s23, 0
	s_add_u32 s12, s12, s6
	s_addc_u32 s13, s13, s7
	s_add_u32 s22, s5, s8
	v_readfirstlane_b32 s5, v40
	s_addc_u32 s23, s21, s9
	s_ashr_i32 s21, s5, 6
	s_and_b32 s24, s21, 1
	v_lshl_or_b32 v28, s21, 3, v28
	v_and_b32_e32 v0, 7, v40
	s_lshl_b32 s25, s24, 2
	v_ashrrev_i32_e32 v29, 31, v28
	v_bitop3_b32 v0, s25, v0, v42 bitop3:0x36
	v_lshlrev_b64 v[28:29], 10, v[28:29]
	v_lshl_add_u64 v[30:31], s[12:13], 0, v[28:29]
	v_lshlrev_b32_e32 v0, 4, v0
	s_lshl_b32 s25, s21, 10
	v_lshl_add_u64 v[30:31], v[30:31], 0, v[0:1]
	s_mov_b32 m0, s25
	s_add_i32 s12, s25, 0x1000
	s_barrier
	global_load_lds_dwordx4 v[30:31], off
	v_lshl_add_u64 v[38:39], v[30:31], 0, s[36:37]
	s_mov_b32 m0, s12
	s_add_i32 s13, s25, 0x2000
	v_lshl_add_u64 v[28:29], s[22:23], 0, v[28:29]
	global_load_lds_dwordx4 v[38:39], off
	v_lshl_add_u64 v[38:39], v[30:31], 0, s[34:35]
	s_mov_b32 m0, s13
	s_add_i32 s21, s25, 0x3000
	s_lshr_b32 s5, s5, 1
	v_and_b32_e32 v41, 15, v40
	v_lshl_add_u64 v[28:29], v[28:29], 0, v[0:1]
	global_load_lds_dwordx4 v[38:39], off
	v_lshl_add_u64 v[38:39], v[30:31], 0, s[38:39]
	s_mov_b32 m0, s21
	v_bfe_u32 v0, v40, 1, 3
	s_and_b32 s5, s5, 0x1ffffc0
	global_load_lds_dwordx4 v[38:39], off
	s_add_i32 s23, s25, 0x4000
	v_or_b32_e32 v38, s5, v41
	v_lshlrev_b32_e32 v39, 7, v41
	v_xor_b32_e32 v43, v42, v0
	v_bitop3_b32 v0, v42, v0, 4 bitop3:0x36
	s_mov_b32 m0, s23
	v_lshlrev_b32_e32 v38, 7, v38
	v_lshl_or_b32 v39, s24, 11, v39
	s_add_i32 s26, s25, 0x8a00
	v_lshlrev_b32_e32 v43, 4, v43
	v_lshlrev_b32_e32 v0, 4, v0
	global_load_lds_dwordx4 v[28:29], off
	v_add_u32_e32 v40, 0x8a00, v38
	v_add_u32_e32 v41, 0x8a00, v39
	s_add_i32 s27, s25, 0x9a00
	s_waitcnt vmcnt(0)
	v_or_b32_e32 v74, v38, v43
	v_or_b32_e32 v75, v39, v43
	v_or_b32_e32 v76, v38, v0
	v_or_b32_e32 v77, v39, v0
	v_lshl_add_u64 v[38:39], v[30:31], 0, s[46:47]
	s_mov_b32 m0, s26
	s_add_i32 s24, s25, 0xaa00
	s_waitcnt vmcnt(0)
	s_waitcnt lgkmcnt(0)
	s_barrier
	global_load_lds_dwordx4 v[38:39], off
	v_lshl_add_u64 v[38:39], v[30:31], 0, s[60:61]
	s_mov_b32 m0, s27
	s_add_i32 s22, s25, 0xba00
	global_load_lds_dwordx4 v[38:39], off
	v_lshl_add_u64 v[38:39], v[30:31], 0, s[54:55]
	s_mov_b32 m0, s24
	s_add_i32 s5, s25, 0xca00
	global_load_lds_dwordx4 v[38:39], off
	v_lshl_add_u64 v[38:39], v[30:31], 0, s[58:59]
	s_mov_b32 m0, s22
	v_or_b32_e32 v78, v40, v43
	global_load_lds_dwordx4 v[38:39], off
	v_lshl_add_u64 v[38:39], v[28:29], 0, s[46:47]
	s_mov_b32 m0, s5
	v_or_b32_e32 v79, v41, v43
	global_load_lds_dwordx4 v[38:39], off
	v_or_b32_e32 v80, v40, v0
	v_or_b32_e32 v0, v41, v0
	ds_read_b128 v[38:41], v74
	ds_read_b128 v[42:45], v74 offset:2048
	ds_read_b128 v[46:49], v74 offset:4096
	ds_read_b128 v[50:53], v74 offset:6144
	ds_read_b128 v[54:57], v75 offset:16384
	s_setprio 1
	s_waitcnt lgkmcnt(0)
	v_mfma_f32_16x16x32_bf16 v[38:41], v[54:57], v[38:41], 0
	v_mfma_f32_16x16x32_bf16 v[42:45], v[54:57], v[42:45], 0
	v_mfma_f32_16x16x32_bf16 v[46:49], v[54:57], v[46:49], 0
	v_mfma_f32_16x16x32_bf16 v[50:53], v[54:57], v[50:53], 0
	s_setprio 0
	ds_read_b128 v[54:57], v76
	ds_read_b128 v[58:61], v76 offset:2048
	ds_read_b128 v[62:65], v76 offset:4096
	ds_read_b128 v[66:69], v76 offset:6144
	ds_read_b128 v[70:73], v77 offset:16384
	s_setprio 1
	s_waitcnt lgkmcnt(0)
	v_mfma_f32_16x16x32_bf16 v[38:41], v[70:73], v[54:57], v[38:41]
	v_mfma_f32_16x16x32_bf16 v[42:45], v[70:73], v[58:61], v[42:45]
	v_mfma_f32_16x16x32_bf16 v[46:49], v[70:73], v[62:65], v[46:49]
	v_mfma_f32_16x16x32_bf16 v[50:53], v[70:73], v[66:69], v[50:53]
	s_setprio 0
	s_mov_b32 m0, s25
	v_lshl_add_u64 v[54:55], v[30:31], 0, s[62:63]
	s_waitcnt vmcnt(0)
	s_waitcnt vmcnt(0)
	s_barrier
	global_load_lds_dwordx4 v[54:55], off
	v_lshl_add_u64 v[54:55], v[30:31], 0, s[56:57]
	s_mov_b32 m0, s12
	s_nop 0
	global_load_lds_dwordx4 v[54:55], off
	v_lshl_add_u64 v[54:55], v[30:31], 0, s[76:77]
	s_mov_b32 m0, s13
	s_nop 0
	global_load_lds_dwordx4 v[54:55], off
	v_lshl_add_u64 v[54:55], v[30:31], 0, s[52:53]
	s_mov_b32 m0, s21
	s_nop 0
	global_load_lds_dwordx4 v[54:55], off
	v_lshl_add_u64 v[54:55], v[28:29], 0, s[62:63]
	s_mov_b32 m0, s23
	s_nop 0
	global_load_lds_dwordx4 v[54:55], off
	ds_read_b128 v[54:57], v78
	ds_read_b128 v[58:61], v78 offset:2048
	ds_read_b128 v[62:65], v78 offset:4096
	ds_read_b128 v[66:69], v78 offset:6144
	ds_read_b128 v[70:73], v79 offset:16384
	s_setprio 1
	s_waitcnt lgkmcnt(0)
	v_mfma_f32_16x16x32_bf16 v[38:41], v[70:73], v[54:57], v[38:41]
	v_mfma_f32_16x16x32_bf16 v[42:45], v[70:73], v[58:61], v[42:45]
	v_mfma_f32_16x16x32_bf16 v[46:49], v[70:73], v[62:65], v[46:49]
	v_mfma_f32_16x16x32_bf16 v[50:53], v[70:73], v[66:69], v[50:53]
	s_setprio 0
	ds_read_b128 v[54:57], v80
	ds_read_b128 v[58:61], v80 offset:2048
	ds_read_b128 v[62:65], v80 offset:4096
	ds_read_b128 v[66:69], v80 offset:6144
	ds_read_b128 v[70:73], v0 offset:16384
	s_setprio 1
	s_waitcnt lgkmcnt(0)
	v_mfma_f32_16x16x32_bf16 v[38:41], v[70:73], v[54:57], v[38:41]
	v_mfma_f32_16x16x32_bf16 v[42:45], v[70:73], v[58:61], v[42:45]
	v_mfma_f32_16x16x32_bf16 v[46:49], v[70:73], v[62:65], v[46:49]
	v_mfma_f32_16x16x32_bf16 v[50:53], v[70:73], v[66:69], v[50:53]
	s_setprio 0
	s_mov_b32 m0, s26
	v_lshl_add_u64 v[54:55], v[30:31], 0, s[40:41]
	s_waitcnt vmcnt(0)
	s_waitcnt vmcnt(0)
	s_barrier
	global_load_lds_dwordx4 v[54:55], off
	v_lshl_add_u64 v[54:55], v[30:31], 0, s[42:43]
	s_mov_b32 m0, s27
	s_mov_b64 s[28:29], 0x10180
	global_load_lds_dwordx4 v[54:55], off
	v_lshl_add_u64 v[54:55], v[30:31], 0, s[28:29]
	s_mov_b32 m0, s24
	s_mov_b64 s[28:29], 0x18180
	global_load_lds_dwordx4 v[54:55], off
	v_lshl_add_u64 v[54:55], v[30:31], 0, s[28:29]
	s_mov_b32 m0, s22
	s_nop 0
	global_load_lds_dwordx4 v[54:55], off
	v_lshl_add_u64 v[54:55], v[28:29], 0, s[40:41]
	s_mov_b32 m0, s5
	s_nop 0
	global_load_lds_dwordx4 v[54:55], off
	ds_read_b128 v[54:57], v74
	ds_read_b128 v[58:61], v74 offset:2048
	ds_read_b128 v[62:65], v74 offset:4096
	ds_read_b128 v[66:69], v74 offset:6144
	ds_read_b128 v[70:73], v75 offset:16384
	s_setprio 1
	s_waitcnt lgkmcnt(0)
	v_mfma_f32_16x16x32_bf16 v[38:41], v[70:73], v[54:57], v[38:41]
	v_mfma_f32_16x16x32_bf16 v[42:45], v[70:73], v[58:61], v[42:45]
	v_mfma_f32_16x16x32_bf16 v[46:49], v[70:73], v[62:65], v[46:49]
	v_mfma_f32_16x16x32_bf16 v[50:53], v[70:73], v[66:69], v[50:53]
	s_setprio 0
	ds_read_b128 v[54:57], v76
	ds_read_b128 v[58:61], v76 offset:2048
	ds_read_b128 v[62:65], v76 offset:4096
	ds_read_b128 v[66:69], v76 offset:6144
	ds_read_b128 v[70:73], v77 offset:16384
	s_setprio 1
	s_waitcnt lgkmcnt(0)
	v_mfma_f32_16x16x32_bf16 v[38:41], v[70:73], v[54:57], v[38:41]
	v_mfma_f32_16x16x32_bf16 v[42:45], v[70:73], v[58:61], v[42:45]
	v_mfma_f32_16x16x32_bf16 v[46:49], v[70:73], v[62:65], v[46:49]
	v_mfma_f32_16x16x32_bf16 v[50:53], v[70:73], v[66:69], v[50:53]
	s_setprio 0
	s_mov_b32 m0, s25
	v_lshl_add_u64 v[54:55], v[30:31], 0, s[90:91]
	s_mov_b64 s[28:29], 0x8200
	s_waitcnt vmcnt(0)
	s_waitcnt vmcnt(0)
	s_barrier
	global_load_lds_dwordx4 v[54:55], off
	v_lshl_add_u64 v[54:55], v[30:31], 0, s[28:29]
	s_mov_b32 m0, s12
	s_mov_b64 s[28:29], 0x10200
	global_load_lds_dwordx4 v[54:55], off
	v_lshl_add_u64 v[54:55], v[30:31], 0, s[28:29]
	s_mov_b32 m0, s13
	s_mov_b64 s[28:29], 0x18200
	global_load_lds_dwordx4 v[54:55], off
	v_lshl_add_u64 v[54:55], v[30:31], 0, s[28:29]
	s_mov_b32 m0, s21
	s_nop 0
	global_load_lds_dwordx4 v[54:55], off
	v_lshl_add_u64 v[54:55], v[28:29], 0, s[90:91]
	s_mov_b32 m0, s23
	s_nop 0
	global_load_lds_dwordx4 v[54:55], off
	ds_read_b128 v[54:57], v78
	ds_read_b128 v[58:61], v78 offset:2048
	ds_read_b128 v[62:65], v78 offset:4096
	ds_read_b128 v[66:69], v78 offset:6144
	ds_read_b128 v[70:73], v79 offset:16384
	s_setprio 1
	s_waitcnt lgkmcnt(0)
	v_mfma_f32_16x16x32_bf16 v[38:41], v[70:73], v[54:57], v[38:41]
	v_mfma_f32_16x16x32_bf16 v[42:45], v[70:73], v[58:61], v[42:45]
	v_mfma_f32_16x16x32_bf16 v[46:49], v[70:73], v[62:65], v[46:49]
	v_mfma_f32_16x16x32_bf16 v[50:53], v[70:73], v[66:69], v[50:53]
	s_setprio 0
	ds_read_b128 v[54:57], v80
	ds_read_b128 v[58:61], v80 offset:2048
	ds_read_b128 v[62:65], v80 offset:4096
	ds_read_b128 v[66:69], v80 offset:6144
	ds_read_b128 v[70:73], v0 offset:16384
	s_setprio 1
	s_waitcnt lgkmcnt(0)
	v_mfma_f32_16x16x32_bf16 v[38:41], v[70:73], v[54:57], v[38:41]
	v_mfma_f32_16x16x32_bf16 v[42:45], v[70:73], v[58:61], v[42:45]
	v_mfma_f32_16x16x32_bf16 v[46:49], v[70:73], v[62:65], v[46:49]
	v_mfma_f32_16x16x32_bf16 v[50:53], v[70:73], v[66:69], v[50:53]
	s_setprio 0
	s_mov_b32 m0, s26
	v_lshl_add_u64 v[54:55], v[30:31], 0, s[44:45]
	s_mov_b64 s[28:29], 0x8280
	s_waitcnt vmcnt(0)
	s_waitcnt vmcnt(0)
	s_barrier
	global_load_lds_dwordx4 v[54:55], off
	v_lshl_add_u64 v[54:55], v[30:31], 0, s[28:29]
	s_mov_b32 m0, s27
	s_mov_b64 s[28:29], 0x10280
	global_load_lds_dwordx4 v[54:55], off
	v_lshl_add_u64 v[54:55], v[30:31], 0, s[28:29]
	s_mov_b32 m0, s24
	s_mov_b64 s[28:29], 0x18280
	global_load_lds_dwordx4 v[54:55], off
	v_lshl_add_u64 v[54:55], v[30:31], 0, s[28:29]
	s_mov_b32 m0, s22
	s_nop 0
	global_load_lds_dwordx4 v[54:55], off
	v_lshl_add_u64 v[54:55], v[28:29], 0, s[44:45]
	s_mov_b32 m0, s5
	s_nop 0
	global_load_lds_dwordx4 v[54:55], off
	ds_read_b128 v[54:57], v74
	ds_read_b128 v[58:61], v74 offset:2048
	ds_read_b128 v[62:65], v74 offset:4096
	ds_read_b128 v[66:69], v74 offset:6144
	ds_read_b128 v[70:73], v75 offset:16384
	s_setprio 1
	s_waitcnt lgkmcnt(0)
	v_mfma_f32_16x16x32_bf16 v[38:41], v[70:73], v[54:57], v[38:41]
	v_mfma_f32_16x16x32_bf16 v[42:45], v[70:73], v[58:61], v[42:45]
	v_mfma_f32_16x16x32_bf16 v[46:49], v[70:73], v[62:65], v[46:49]
	v_mfma_f32_16x16x32_bf16 v[50:53], v[70:73], v[66:69], v[50:53]
	s_setprio 0
	ds_read_b128 v[54:57], v76
	ds_read_b128 v[58:61], v76 offset:2048
	ds_read_b128 v[62:65], v76 offset:4096
	ds_read_b128 v[66:69], v76 offset:6144
	ds_read_b128 v[70:73], v77 offset:16384
	s_setprio 1
	s_waitcnt lgkmcnt(0)
	v_mfma_f32_16x16x32_bf16 v[38:41], v[70:73], v[54:57], v[38:41]
	v_mfma_f32_16x16x32_bf16 v[42:45], v[70:73], v[58:61], v[42:45]
	v_mfma_f32_16x16x32_bf16 v[46:49], v[70:73], v[62:65], v[46:49]
	v_mfma_f32_16x16x32_bf16 v[50:53], v[70:73], v[66:69], v[50:53]
	s_setprio 0
	s_mov_b32 m0, s25
	v_lshl_add_u64 v[54:55], v[30:31], 0, s[48:49]
	s_mov_b64 s[28:29], 0x8300
	s_waitcnt vmcnt(0)
	s_waitcnt vmcnt(0)
	s_barrier
	global_load_lds_dwordx4 v[54:55], off
	v_lshl_add_u64 v[54:55], v[30:31], 0, s[28:29]
	s_mov_b32 m0, s12
	s_mov_b64 s[28:29], 0x10300
	global_load_lds_dwordx4 v[54:55], off
	v_lshl_add_u64 v[54:55], v[30:31], 0, s[28:29]
	s_mov_b32 m0, s13
	s_mov_b64 s[12:13], 0x18300
	global_load_lds_dwordx4 v[54:55], off
	v_lshl_add_u64 v[54:55], v[30:31], 0, s[12:13]
	s_mov_b32 m0, s21
	s_nop 0
	global_load_lds_dwordx4 v[54:55], off
	v_lshl_add_u64 v[54:55], v[28:29], 0, s[48:49]
	s_mov_b32 m0, s23
	s_nop 0
	global_load_lds_dwordx4 v[54:55], off
	ds_read_b128 v[54:57], v78
	ds_read_b128 v[58:61], v78 offset:2048
	ds_read_b128 v[62:65], v78 offset:4096
	ds_read_b128 v[66:69], v78 offset:6144
	ds_read_b128 v[70:73], v79 offset:16384
	s_setprio 1
	s_waitcnt lgkmcnt(0)
	v_mfma_f32_16x16x32_bf16 v[38:41], v[70:73], v[54:57], v[38:41]
	v_mfma_f32_16x16x32_bf16 v[42:45], v[70:73], v[58:61], v[42:45]
	v_mfma_f32_16x16x32_bf16 v[46:49], v[70:73], v[62:65], v[46:49]
	v_mfma_f32_16x16x32_bf16 v[50:53], v[70:73], v[66:69], v[50:53]
	s_setprio 0
	ds_read_b128 v[54:57], v80
	ds_read_b128 v[58:61], v80 offset:2048
	ds_read_b128 v[62:65], v80 offset:4096
	ds_read_b128 v[66:69], v80 offset:6144
	ds_read_b128 v[70:73], v0 offset:16384
	s_setprio 1
	s_waitcnt lgkmcnt(0)
	v_mfma_f32_16x16x32_bf16 v[38:41], v[70:73], v[54:57], v[38:41]
	v_mfma_f32_16x16x32_bf16 v[42:45], v[70:73], v[58:61], v[42:45]
	v_mfma_f32_16x16x32_bf16 v[46:49], v[70:73], v[62:65], v[46:49]
	v_mfma_f32_16x16x32_bf16 v[50:53], v[70:73], v[66:69], v[50:53]
	s_setprio 0
	s_mov_b32 m0, s26
	v_lshl_add_u64 v[54:55], v[30:31], 0, s[50:51]
	s_mov_b64 s[12:13], 0x8380
	s_waitcnt vmcnt(0)
	s_waitcnt vmcnt(0)
	s_barrier
	global_load_lds_dwordx4 v[54:55], off
	v_lshl_add_u64 v[54:55], v[30:31], 0, s[12:13]
	s_mov_b32 m0, s27
	s_mov_b64 s[12:13], 0x10380
	global_load_lds_dwordx4 v[54:55], off
	v_lshl_add_u64 v[54:55], v[30:31], 0, s[12:13]
	s_mov_b32 m0, s24
	s_mov_b64 s[12:13], 0x18380
	global_load_lds_dwordx4 v[54:55], off
	v_lshl_add_u64 v[30:31], v[30:31], 0, s[12:13]
	s_mov_b32 m0, s22
	v_lshl_add_u64 v[28:29], v[28:29], 0, s[50:51]
	global_load_lds_dwordx4 v[30:31], off
	s_mov_b32 m0, s5
	s_nop 0
	global_load_lds_dwordx4 v[28:29], off
	ds_read_b128 v[28:31], v74
	ds_read_b128 v[54:57], v74 offset:2048
	ds_read_b128 v[58:61], v74 offset:4096
	ds_read_b128 v[62:65], v74 offset:6144
	ds_read_b128 v[66:69], v75 offset:16384
	s_setprio 1
	s_waitcnt lgkmcnt(0)
	v_mfma_f32_16x16x32_bf16 v[28:31], v[66:69], v[28:31], v[38:41]
	v_mfma_f32_16x16x32_bf16 v[38:41], v[66:69], v[54:57], v[42:45]
	v_mfma_f32_16x16x32_bf16 v[42:45], v[66:69], v[58:61], v[46:49]
	v_mfma_f32_16x16x32_bf16 v[46:49], v[66:69], v[62:65], v[50:53]
	s_setprio 0
	s_nop 1
	ds_read_b128 v[50:53], v76
	ds_read_b128 v[54:57], v76 offset:2048
	ds_read_b128 v[58:61], v76 offset:4096
	ds_read_b128 v[62:65], v76 offset:6144
	ds_read_b128 v[66:69], v77 offset:16384
	s_setprio 1
	s_waitcnt lgkmcnt(0)
	v_mfma_f32_16x16x32_bf16 v[28:31], v[66:69], v[50:53], v[28:31]
	v_mfma_f32_16x16x32_bf16 v[38:41], v[66:69], v[54:57], v[38:41]
	v_mfma_f32_16x16x32_bf16 v[42:45], v[66:69], v[58:61], v[42:45]
	v_mfma_f32_16x16x32_bf16 v[46:49], v[66:69], v[62:65], v[46:49]
	s_setprio 0
	s_waitcnt vmcnt(0)
	s_waitcnt vmcnt(0)
	s_barrier
	ds_read_b128 v[50:53], v79 offset:16384
	ds_read_b128 v[54:57], v78 offset:6144
	ds_read_b128 v[58:61], v78 offset:4096
	ds_read_b128 v[62:65], v78 offset:2048
	ds_read_b128 v[66:69], v78
	s_setprio 1
	s_waitcnt lgkmcnt(0)
	v_mfma_f32_16x16x32_bf16 v[28:31], v[50:53], v[66:69], v[28:31]
	v_mfma_f32_16x16x32_bf16 v[38:41], v[50:53], v[62:65], v[38:41]
	v_mfma_f32_16x16x32_bf16 v[42:45], v[50:53], v[58:61], v[42:45]
	v_mfma_f32_16x16x32_bf16 v[46:49], v[50:53], v[54:57], v[46:49]
	s_setprio 0
	ds_read_b128 v[50:53], v80
	ds_read_b128 v[54:57], v80 offset:2048
	ds_read_b128 v[58:61], v80 offset:4096
	ds_read_b128 v[62:65], v80 offset:6144
	ds_read_b128 v[66:69], v0 offset:16384
	s_setprio 1
	s_waitcnt lgkmcnt(0)
	v_mfma_f32_16x16x32_bf16 v[28:31], v[66:69], v[50:53], v[28:31]
	v_mfma_f32_16x16x32_bf16 v[38:41], v[66:69], v[54:57], v[38:41]
	v_mfma_f32_16x16x32_bf16 v[42:45], v[66:69], v[58:61], v[42:45]
	v_mfma_f32_16x16x32_bf16 v[46:49], v[66:69], v[62:65], v[46:49]
	s_setprio 0
	s_load_dwordx2 s[12:13], s[0:1], 0x198
	s_waitcnt lgkmcnt(0)
	v_lshl_add_u64 v[82:83], s[12:13], 0, v[26:27]
	v_lshl_add_u64 v[82:83], v[82:83], 0, s[10:11]
	v_lshl_add_u64 v[84:85], s[12:13], 0, v[24:25]
	v_lshl_add_u64 v[84:85], v[84:85], 0, s[10:11]
	v_lshl_add_u64 v[86:87], s[12:13], 0, v[22:23]
	v_lshl_add_u64 v[86:87], v[86:87], 0, s[10:11]
	v_lshl_add_u64 v[88:89], s[12:13], 0, v[20:21]
	v_lshl_add_u64 v[88:89], v[88:89], 0, s[10:11]
	global_load_dwordx2 v[90:91], v[82:83], off
	global_load_dwordx2 v[92:93], v[84:85], off
	global_load_dwordx2 v[94:95], v[86:87], off
	global_load_dwordx2 v[96:97], v[88:89], off
	s_add_u32 s10, s10, 0x800
	s_addc_u32 s11, s11, 0
	s_cmpk_eq_i32 s10, 0x1800
	s_waitcnt vmcnt(3)
	v_lshlrev_b32_e32 v98, 16, v90
	v_and_b32_e32 v99, 0xffff0000, v90
	v_lshlrev_b32_e32 v100, 16, v91
	v_and_b32_e32 v101, 0xffff0000, v91
	v_pk_fma_f32 v[16:17], v[28:29], v[98:99], v[16:17]
	v_pk_fma_f32 v[18:19], v[30:31], v[100:101], v[18:19]
	s_waitcnt vmcnt(2)
	v_lshlrev_b32_e32 v98, 16, v92
	v_and_b32_e32 v99, 0xffff0000, v92
	v_lshlrev_b32_e32 v100, 16, v93
	v_and_b32_e32 v101, 0xffff0000, v93
	v_pk_fma_f32 v[12:13], v[38:39], v[98:99], v[12:13]
	v_pk_fma_f32 v[14:15], v[40:41], v[100:101], v[14:15]
	s_waitcnt vmcnt(1)
	v_lshlrev_b32_e32 v98, 16, v94
	v_and_b32_e32 v99, 0xffff0000, v94
	v_lshlrev_b32_e32 v100, 16, v95
	v_and_b32_e32 v101, 0xffff0000, v95
	v_pk_fma_f32 v[8:9], v[42:43], v[98:99], v[8:9]
	v_pk_fma_f32 v[10:11], v[44:45], v[100:101], v[10:11]
	s_waitcnt vmcnt(0)
	v_lshlrev_b32_e32 v98, 16, v96
	v_and_b32_e32 v99, 0xffff0000, v96
	v_lshlrev_b32_e32 v100, 16, v97
	v_and_b32_e32 v101, 0xffff0000, v97
	v_pk_fma_f32 v[6:7], v[46:47], v[98:99], v[6:7]
	v_pk_fma_f32 v[2:3], v[48:49], v[100:101], v[2:3]
	s_cbranch_scc0 .LBB0_2047
	v_lshl_add_u32 v20, s4, 7, v32
	s_load_dwordx2 s[4:5], s[0:1], 0x1b8
	v_ashrrev_i32_e32 v21, 31, v20
	v_or_b32_e32 v22, 16, v20
	v_or_b32_e32 v24, 32, v20
	v_or_b32_e32 v26, 48, v20
	s_waitcnt lgkmcnt(0)
	v_lshl_add_u64 v[4:5], v[4:5], 1, s[4:5]
	v_lshlrev_b64 v[20:21], 11, v[20:21]
	v_ashrrev_i32_e32 v23, 31, v22
	v_lshl_add_u64 v[20:21], v[4:5], 0, v[20:21]
	v_cvt_pk_bf16_f32 v16, v16, v17
	v_cvt_pk_bf16_f32 v17, v18, v19
	global_store_dwordx2 v[20:21], v[16:17], off
	v_lshlrev_b64 v[16:17], 11, v[22:23]
	v_ashrrev_i32_e32 v25, 31, v24
	v_lshl_add_u64 v[16:17], v[4:5], 0, v[16:17]
	v_cvt_pk_bf16_f32 v12, v12, v13
	v_cvt_pk_bf16_f32 v13, v14, v15
	global_store_dwordx2 v[16:17], v[12:13], off
	v_lshlrev_b64 v[12:13], 11, v[24:25]
	v_ashrrev_i32_e32 v27, 31, v26
	v_lshl_add_u64 v[12:13], v[4:5], 0, v[12:13]
	v_cvt_pk_bf16_f32 v8, v8, v9
	v_cvt_pk_bf16_f32 v9, v10, v11
	global_store_dwordx2 v[12:13], v[8:9], off
	v_lshlrev_b64 v[8:9], 11, v[26:27]
	s_add_i32 s16, s16, s17
	v_lshl_add_u64 v[4:5], v[4:5], 0, v[8:9]
	v_cvt_pk_bf16_f32 v6, v6, v7
	v_cvt_pk_bf16_f32 v7, v2, v3
	s_cmp_ge_i32 s16, s18
	global_store_dwordx2 v[4:5], v[6:7], off
	s_cbranch_scc0 .LBB0_2042
